# grid barrier: non-leader workgroups poll the top release generation directly instead of the per-XCC generation
# speedup vs baseline: 1.0153x; 1.0030x over previous
; __device__ __forceinline__ unsigned xb_ld(unsigned* p)              { return __hip_atomic_load(p, __ATOMIC_RELAXED, __HIP_MEMORY_SCOPE_AGENT); }
; __device__ __forceinline__ unsigned xb_add(unsigned* p, unsigned v) { return __hip_atomic_fetch_add(p, v, __ATOMIC_RELAXED, __HIP_MEMORY_SCOPE_AGENT); }
; #define XB_SPIN(cond, bar) do { unsigned _sp = 0; while (cond) { __builtin_amdgcn_s_sleep(1); \
;     if ((++_sp & 255u) == 0u) { if (xb_ld(&(bar)[XB_TMO])) break; if (_sp > XB_SPIN_CAP) { atomicAdd(&(bar)[XB_TMO], 1u); break; } } } } while (0)
; __device__ __forceinline__ void xcd_barrier(const XcdBarrier& b) {
;     asm volatile("s_waitcnt vmcnt(0)" ::: "memory");
;     __syncthreads();
;     if (threadIdx.x == 0) {
;         unsigned* bar = b.bar;
;         __builtin_amdgcn_s_waitcnt(0);
;         unsigned nloc = b.st[0], nx = b.st[1];
;         if (nloc == 0u) { xcd_barrier_complete(bar, b.x, nloc, nx); b.st[0] = nloc; b.st[1] = nx; }
;         const unsigned old = xb_add(&bar[XB_XSUB(b.x)], 1u);
;         const unsigned gen = old / nloc;
;         if (old + 1u == (gen + 1u) * nloc) {
;             __builtin_amdgcn_fence(__ATOMIC_RELEASE, "agent");
;             asm volatile("s_waitcnt vmcnt(0)" ::: "memory");
;             const unsigned og = xb_add(&bar[XB_TOP], 1u);
;             const unsigned tg = og / nx;
;             if (og + 1u == (tg + 1u) * nx) xb_add(&bar[XB_TOPGEN], 1u);
;             else XB_SPIN(xb_ld(&bar[XB_TOPGEN]) == tg, bar);
;             __builtin_amdgcn_fence(__ATOMIC_ACQUIRE, "agent");
;             xb_add(&bar[XB_XGEN(b.x)], 1u);
;             asm volatile("s_waitcnt vmcnt(0)" ::: "memory");
;         } else {
;             XB_SPIN(xb_ld(&bar[XB_XGEN(b.x)]) == gen, bar);
;             __builtin_amdgcn_fence(__ATOMIC_ACQUIRE, "agent");
;             asm volatile("s_waitcnt vmcnt(0)" ::: "memory");
;         }
.LBB0_101:
	s_or_b64 exec, exec, s[38:39]
	v_cvt_f32_u32_e32 v5, v3
	s_waitcnt vmcnt(0)
	v_readfirstlane_b32 s2, v4
	v_sub_u32_e32 v4, 0, v3
	v_rcp_iflag_f32_e32 v5, v5
	v_add_u32_e32 v6, s2, v1
	v_mul_f32_e32 v5, 0x4f7ffffe, v5
	v_cvt_u32_f32_e32 v5, v5
	v_mul_lo_u32 v1, v4, v5
	v_mul_hi_u32 v1, v5, v1
	v_add_u32_e32 v1, v5, v1
	v_mul_hi_u32 v1, v6, v1
	v_mul_lo_u32 v4, v1, v3
	v_sub_u32_e32 v4, v6, v4
	v_add_u32_e32 v5, 1, v1
	v_cmp_ge_u32_e32 vcc, v4, v3
	s_nop 1
	v_cndmask_b32_e32 v1, v1, v5, vcc
	v_sub_u32_e32 v5, v4, v3
	v_cndmask_b32_e32 v4, v4, v5, vcc
	v_add_u32_e32 v5, 1, v1
	v_cmp_ge_u32_e32 vcc, v4, v3
	v_add_u32_e32 v4, 1, v6
	s_nop 0
	v_cndmask_b32_e32 v1, v1, v5, vcc
	v_mul_lo_u32 v5, v3, v1
	v_add_u32_e32 v3, v5, v3
	v_cmp_ne_u32_e32 vcc, v4, v3
	s_and_saveexec_b64 s[20:21], vcc
	s_xor_b64 s[38:39], exec, s[20:21]
	s_cbranch_execz .LBB0_115
	v_readlane_b32 s20, v252, 29
	v_readlane_b32 s21, v252, 30
	s_waitcnt lgkmcnt(0)
	s_nop 3
	global_load_dword v2, v0, s[20:21] sc1
	s_waitcnt vmcnt(0)
	v_cmp_eq_u32_e32 vcc, v2, v1
	s_and_saveexec_b64 s[40:41], vcc
	s_cbranch_execz .LBB0_114
	s_mov_b32 s2, 1
	s_mov_b64 s[42:43], 0
	s_branch .LBB0_105

; __device__ __forceinline__ unsigned xb_ld(unsigned* p)              { return __hip_atomic_load(p, __ATOMIC_RELAXED, __HIP_MEMORY_SCOPE_AGENT); }
; __device__ __forceinline__ unsigned xb_add(unsigned* p, unsigned v) { return __hip_atomic_fetch_add(p, v, __ATOMIC_RELAXED, __HIP_MEMORY_SCOPE_AGENT); }
; #define XB_SPIN(cond, bar) do { unsigned _sp = 0; while (cond) { __builtin_amdgcn_s_sleep(1); \
;     if ((++_sp & 255u) == 0u) { if (xb_ld(&(bar)[XB_TMO])) break; if (_sp > XB_SPIN_CAP) { atomicAdd(&(bar)[XB_TMO], 1u); break; } } } } while (0)
; __device__ __forceinline__ void xcd_barrier(const XcdBarrier& b) {
;     asm volatile("s_waitcnt vmcnt(0)" ::: "memory");
;     __syncthreads();
;     if (threadIdx.x == 0) {
;         unsigned* bar = b.bar;
;         __builtin_amdgcn_s_waitcnt(0);
;         unsigned nloc = b.st[0], nx = b.st[1];
;         if (nloc == 0u) { xcd_barrier_complete(bar, b.x, nloc, nx); b.st[0] = nloc; b.st[1] = nx; }
;         const unsigned old = xb_add(&bar[XB_XSUB(b.x)], 1u);
;         const unsigned gen = old / nloc;
;         if (old + 1u == (gen + 1u) * nloc) {
;             __builtin_amdgcn_fence(__ATOMIC_RELEASE, "agent");
;             asm volatile("s_waitcnt vmcnt(0)" ::: "memory");
;             const unsigned og = xb_add(&bar[XB_TOP], 1u);
;             const unsigned tg = og / nx;
;             if (og + 1u == (tg + 1u) * nx) xb_add(&bar[XB_TOPGEN], 1u);
;             else XB_SPIN(xb_ld(&bar[XB_TOPGEN]) == tg, bar);
;             __builtin_amdgcn_fence(__ATOMIC_ACQUIRE, "agent");
;             xb_add(&bar[XB_XGEN(b.x)], 1u);
;             asm volatile("s_waitcnt vmcnt(0)" ::: "memory");
;         } else {
;             XB_SPIN(xb_ld(&bar[XB_XGEN(b.x)]) == gen, bar);
;             __builtin_amdgcn_fence(__ATOMIC_ACQUIRE, "agent");
;             asm volatile("s_waitcnt vmcnt(0)" ::: "memory");
;         }
.LBB0_826:
	s_or_b64 exec, exec, s[38:39]
	v_cvt_f32_u32_e32 v5, v3
	s_waitcnt vmcnt(0)
	v_readfirstlane_b32 s2, v4
	v_sub_u32_e32 v4, 0, v3
	v_rcp_iflag_f32_e32 v5, v5
	v_add_u32_e32 v6, s2, v1
	v_mul_f32_e32 v5, 0x4f7ffffe, v5
	v_cvt_u32_f32_e32 v5, v5
	v_mul_lo_u32 v1, v4, v5
	v_mul_hi_u32 v1, v5, v1
	v_add_u32_e32 v1, v5, v1
	v_mul_hi_u32 v1, v6, v1
	v_mul_lo_u32 v4, v1, v3
	v_sub_u32_e32 v4, v6, v4
	v_add_u32_e32 v5, 1, v1
	v_cmp_ge_u32_e32 vcc, v4, v3
	s_nop 1
	v_cndmask_b32_e32 v1, v1, v5, vcc
	v_sub_u32_e32 v5, v4, v3
	v_cndmask_b32_e32 v4, v4, v5, vcc
	v_add_u32_e32 v5, 1, v1
	v_cmp_ge_u32_e32 vcc, v4, v3
	v_add_u32_e32 v4, 1, v6
	s_nop 0
	v_cndmask_b32_e32 v1, v1, v5, vcc
	v_mul_lo_u32 v5, v3, v1
	v_add_u32_e32 v3, v5, v3
	v_cmp_ne_u32_e32 vcc, v4, v3
	s_and_saveexec_b64 s[20:21], vcc
	s_xor_b64 s[38:39], exec, s[20:21]
	s_cbranch_execz .LBB0_840
	v_readlane_b32 s20, v252, 29
	v_readlane_b32 s21, v252, 30
	s_waitcnt lgkmcnt(0)
	s_nop 3
	global_load_dword v2, v0, s[20:21] sc1
	s_waitcnt vmcnt(0)
	v_cmp_eq_u32_e32 vcc, v2, v1
	s_and_saveexec_b64 s[42:43], vcc
	s_cbranch_execz .LBB0_839
	s_mov_b32 s2, 1
	s_mov_b64 s[44:45], 0
	s_branch .LBB0_830
